# ph9 quarter-tile tail with the four quarters of a tile on workgroups of the same XCD
# baseline (speedup 1.0000x reference)
.LBB0_249:
	s_add_i32 s71, s71, 1
	s_mul_i32 s18, s71, s15
	s_mul_hi_u32 s19, s71, s64
	s_add_i32 s19, s19, s18
	s_mul_i32 s18, s71, s64
	s_add_u32 s18, s18, s16
	s_addc_u32 s19, s19, s39
	s_mov_b32 s101, 0
	s_cmp_lg_u32 s71, 1
	s_cbranch_scc1 .Lh9_a
	s_bfe_u32 s101, s16, 0x10004
	s_add_i32 s101, s101, 5
	s_bfe_u32 s18, s16, 0x10003
	s_lshl_b32 s18, s18, 3
	s_or_b32 s101, s101, s18
	s_lshr_b32 s18, s16, 5
	s_lshl_b32 s18, s18, 3
	s_and_b32 s19, s16, 7
	s_or_b32 s18, s18, s19
	s_mov_b32 s19, 0
	s_addk_i32 s18, 0x100
